# P5 MoBA partial merge loop hand-written: the LSE quad and the 4 partials of an item loaded together and one item ahead (was up to 5 exposed round trips per item)
# speedup vs baseline: 1.0192x; 1.0111x over previous
; DI unsigned pack2bf(float a, float b) { const f2_t v = {a, b}; return __builtin_bit_cast(unsigned, __builtin_convertvector(v, bf2_t)); }
; DI void phase5(const Params& P, char* smem) {
;     ...
;   for (long idx = (long)VB * 256 + VT; idx < (long)NTOK * 64; idx += (long)NVB * 256) {
;     const int dg = (int)idx & 7, h = (int)(idx >> 3) & 7; const long tok = idx >> 6;
;     const int l = (int)(tok & 8191); const int ownb = l >> 8; const int nv = ownb < 3 ? ownb : 3;
;     const long base = (tok * 8 + h) * 4;
;     float ls[4]; float mx = -3e38f;
; #pragma unroll
;     for (int s = 0; s < 4; ++s) { const bool ok = (s == 3) || (s < nv); ls[s] = ok ? Lse[base + s] : -3e38f; mx = fmaxf(mx, ls[s]); }
;     float acc[8]; float wsum = 0.f;
; #pragma unroll
;     for (int k = 0; k < 8; ++k) acc[k] = 0.f;
; #pragma unroll
;     for (int s = 0; s < 4; ++s) {
;       const bool ok = (s == 3) || (s < nv);
;       if (ok) {
;         const float w = __expf(ls[s] - mx); wsum += w;
;         uint4 o = *reinterpret_cast<const uint4*>(Opart + (base + s) * 64 + dg * 8);
;         acc[0] += w * __uint_as_float(o.x << 16); acc[1] += w * __uint_as_float(o.x & 0xffff0000u);
;         acc[2] += w * __uint_as_float(o.y << 16); acc[3] += w * __uint_as_float(o.y & 0xffff0000u);
;         acc[4] += w * __uint_as_float(o.z << 16); acc[5] += w * __uint_as_float(o.z & 0xffff0000u);
;         acc[6] += w * __uint_as_float(o.w << 16); acc[7] += w * __uint_as_float(o.w & 0xffff0000u);
;       }
;     }
;     const float inv = 1.f / wsum;
;     *reinterpret_cast<uint4*>(cat + tok * 1024 + 512 + h * 64 + dg * 8) =
;         make_uint4(pack2bf(acc[0] * inv, acc[1] * inv), pack2bf(acc[2] * inv, acc[3] * inv), pack2bf(acc[4] * inv, acc[5] * inv), pack2bf(acc[6] * inv, acc[7] * inv));
;   }
.LBB0_875:
	s_add_u32 s40, s78, 0x10000000
	s_mov_b64 s[0:1], 0x200000
	s_addc_u32 s41, s79, 0
	v_cmp_gt_i64_e32 vcc, s[0:1], v[128:129]
	s_and_saveexec_b64 s[10:11], vcc
	s_cbranch_execz .LBB0_892
	v_lshlrev_b32_e32 v0, 3, v189
	v_and_b32_e32 v2, 56, v0
	v_mov_b32_e32 v0, 0
	v_lshlrev_b32_e32 v4, 1, v2
	v_mov_b32_e32 v5, v0
	v_lshl_add_u64 v[4:5], s[78:79], 0, v[4:5]
	s_mov_b64 s[0:1], 0x8000000
	v_lshl_add_u64 v[10:11], v[4:5], 0, s[0:1]
	s_mov_b64 s[12:13], 0
	s_mov_b32 s2, 0xff61b1e6
	v_lshlrev_b32_e32 v12, 1, v2
	s_mov_b64 s[14:15], 0x1fffff
	v_mov_b64_e32 v[14:15], v[128:129]
	v_ashrrev_i64 v[16:17], 6, v[14:15]
	v_bfe_u32 v13, v14, 3, 3
	v_lshlrev_b64 v[20:21], 5, v[16:17]
	v_bfe_u32 v232, v16, 8, 5
	v_lshl_or_b32 v20, v13, 2, v20
	v_lshl_add_u64 v[22:23], v[20:21], 2, s[40:41]
	v_lshlrev_b64 v[18:19], 7, v[20:21]
	global_load_dwordx4 v[210:213], v[22:23], off
	v_lshl_add_u64 v[18:19], v[10:11], 0, v[18:19]
	global_load_dwordx4 v[214:217], v[18:19], off
	global_load_dwordx4 v[218:221], v[18:19], off offset:128
	global_load_dwordx4 v[222:225], v[18:19], off offset:256
	global_load_dwordx4 v[226:229], v[18:19], off offset:384
	v_lshlrev_b64 v[16:17], 11, v[16:17]
	v_lshlrev_b32_e32 v24, 7, v13
	v_mov_b32_e32 v25, v0
	v_lshl_add_u64 v[16:17], s[62:63], 0, v[16:17]
	v_mov_b32_e32 v13, v0
	v_lshl_add_u64 v[16:17], v[16:17], 0, v[24:25]
	v_lshl_add_u64 v[230:231], v[16:17], 0, v[12:13]
	v_lshl_add_u64 v[14:15], v[14:15], 0, s[66:67]
	s_mov_b32 s12, 7
	v_ashrrev_i64 v[16:17], 6, v[14:15]
	v_bfe_u32 v13, v14, 3, 3
	v_lshlrev_b64 v[20:21], 5, v[16:17]
	v_bfe_u32 v38, v16, 8, 5
	v_lshl_or_b32 v20, v13, 2, v20
	v_lshl_add_u64 v[22:23], v[20:21], 2, s[40:41]
	v_lshlrev_b64 v[18:19], 7, v[20:21]
	global_load_dwordx4 v[234:237], v[22:23], off
	v_lshl_add_u64 v[18:19], v[10:11], 0, v[18:19]
	global_load_dwordx4 v[238:241], v[18:19], off
	global_load_dwordx4 v[242:245], v[18:19], off offset:128
	global_load_dwordx4 v[246:249], v[18:19], off offset:256
	global_load_dwordx4 v[250:253], v[18:19], off offset:384
	v_lshlrev_b64 v[16:17], 11, v[16:17]
	v_lshlrev_b32_e32 v24, 7, v13
	v_mov_b32_e32 v25, v0
	v_lshl_add_u64 v[16:17], s[62:63], 0, v[16:17]
	v_mov_b32_e32 v13, v0
	v_lshl_add_u64 v[16:17], v[16:17], 0, v[24:25]
	v_lshl_add_u64 v[36:37], v[16:17], 0, v[12:13]
	v_lshl_add_u64 v[14:15], v[14:15], 0, s[66:67]
	s_waitcnt vmcnt(5)
	v_cmp_ne_u32_e64 s[4:5], 0, v232
	v_cmp_lt_u32_e64 s[6:7], 1, v232
	v_cmp_lt_u32_e64 s[8:9], 2, v232
	v_mov_b32_e32 v26, 0xff61b1e6
	v_cndmask_b32_e64 v27, v26, v210, s[4:5]
	v_cndmask_b32_e64 v28, v26, v211, s[6:7]
	v_cndmask_b32_e64 v29, v26, v212, s[8:9]
	v_max3_f32 v24, v27, s2, v28
	v_max3_f32 v24, v24, v29, v213
	v_sub_f32_e32 v1, v27, v24
	v_mul_f32_e32 v1, 0x3fb8aa3b, v1
	v_exp_f32_e32 v30, v1
	v_sub_f32_e32 v1, v28, v24
	v_mul_f32_e32 v1, 0x3fb8aa3b, v1
	v_exp_f32_e32 v32, v1
	v_sub_f32_e32 v1, v29, v24
	v_mul_f32_e32 v1, 0x3fb8aa3b, v1
	v_exp_f32_e32 v34, v1
	v_sub_f32_e32 v1, v213, v24
	v_mul_f32_e32 v1, 0x3fb8aa3b, v1
	v_exp_f32_e32 v48, v1
	v_cndmask_b32_e64 v214, 0, v214, s[4:5]
	v_cndmask_b32_e64 v215, 0, v215, s[4:5]
	v_cndmask_b32_e64 v216, 0, v216, s[4:5]
	v_cndmask_b32_e64 v217, 0, v217, s[4:5]
	v_cndmask_b32_e64 v218, 0, v218, s[6:7]
	v_cndmask_b32_e64 v219, 0, v219, s[6:7]
	v_cndmask_b32_e64 v220, 0, v220, s[6:7]
	v_cndmask_b32_e64 v221, 0, v221, s[6:7]
	v_cndmask_b32_e64 v222, 0, v222, s[8:9]
	v_cndmask_b32_e64 v223, 0, v223, s[8:9]
	v_cndmask_b32_e64 v224, 0, v224, s[8:9]
	v_cndmask_b32_e64 v225, 0, v225, s[8:9]
	v_add_f32_e32 v22, 0, v30
	v_add_f32_e32 v22, v32, v22
	v_add_f32_e32 v22, v34, v22
	v_add_f32_e32 v22, v48, v22
	v_lshlrev_b32_e32 v40, 16, v214
	v_and_b32_e32 v41, 0xffff0000, v214
	v_lshlrev_b32_e32 v42, 16, v215
	v_and_b32_e32 v43, 0xffff0000, v215
	v_lshlrev_b32_e32 v44, 16, v216
	v_and_b32_e32 v45, 0xffff0000, v216
	v_lshlrev_b32_e32 v46, 16, v217
	v_and_b32_e32 v47, 0xffff0000, v217
	v_pk_fma_f32 v[2:3], v[30:31], v[40:41], 0 op_sel_hi:[0,1,0]
	v_pk_fma_f32 v[4:5], v[30:31], v[42:43], 0 op_sel_hi:[0,1,0]
	v_pk_fma_f32 v[6:7], v[30:31], v[44:45], 0 op_sel_hi:[0,1,0]
	v_pk_fma_f32 v[8:9], v[30:31], v[46:47], 0 op_sel_hi:[0,1,0]
	v_lshlrev_b32_e32 v40, 16, v218
	v_and_b32_e32 v41, 0xffff0000, v218
	v_lshlrev_b32_e32 v42, 16, v219
	v_and_b32_e32 v43, 0xffff0000, v219
	v_lshlrev_b32_e32 v44, 16, v220
	v_and_b32_e32 v45, 0xffff0000, v220
	v_lshlrev_b32_e32 v46, 16, v221
	v_and_b32_e32 v47, 0xffff0000, v221
	v_pk_fma_f32 v[2:3], v[32:33], v[40:41], v[2:3] op_sel_hi:[0,1,1]
	v_pk_fma_f32 v[4:5], v[32:33], v[42:43], v[4:5] op_sel_hi:[0,1,1]
	v_pk_fma_f32 v[6:7], v[32:33], v[44:45], v[6:7] op_sel_hi:[0,1,1]
	v_pk_fma_f32 v[8:9], v[32:33], v[46:47], v[8:9] op_sel_hi:[0,1,1]
	v_lshlrev_b32_e32 v40, 16, v222
	v_and_b32_e32 v41, 0xffff0000, v222
	v_lshlrev_b32_e32 v42, 16, v223
	v_and_b32_e32 v43, 0xffff0000, v223
	v_lshlrev_b32_e32 v44, 16, v224
	v_and_b32_e32 v45, 0xffff0000, v224
	v_lshlrev_b32_e32 v46, 16, v225
	v_and_b32_e32 v47, 0xffff0000, v225
	v_pk_fma_f32 v[2:3], v[34:35], v[40:41], v[2:3] op_sel_hi:[0,1,1]
	v_pk_fma_f32 v[4:5], v[34:35], v[42:43], v[4:5] op_sel_hi:[0,1,1]
	v_pk_fma_f32 v[6:7], v[34:35], v[44:45], v[6:7] op_sel_hi:[0,1,1]
	v_pk_fma_f32 v[8:9], v[34:35], v[46:47], v[8:9] op_sel_hi:[0,1,1]
	v_lshlrev_b32_e32 v40, 16, v226
	v_and_b32_e32 v41, 0xffff0000, v226
	v_lshlrev_b32_e32 v42, 16, v227
	v_and_b32_e32 v43, 0xffff0000, v227
	v_lshlrev_b32_e32 v44, 16, v228
	v_and_b32_e32 v45, 0xffff0000, v228
	v_lshlrev_b32_e32 v46, 16, v229
	v_and_b32_e32 v47, 0xffff0000, v229
	v_pk_fma_f32 v[2:3], v[48:49], v[40:41], v[2:3] op_sel_hi:[0,1,1]
	v_pk_fma_f32 v[4:5], v[48:49], v[42:43], v[4:5] op_sel_hi:[0,1,1]
	v_pk_fma_f32 v[6:7], v[48:49], v[44:45], v[6:7] op_sel_hi:[0,1,1]
	v_pk_fma_f32 v[8:9], v[48:49], v[46:47], v[8:9] op_sel_hi:[0,1,1]
	v_mov_b32_e32 v1, v22
	v_div_scale_f32 v22, s[4:5], v1, v1, 1.0
	v_rcp_f32_e32 v23, v22
	s_nop 0
	v_fma_f32 v24, -v22, v23, 1.0
	v_div_scale_f32 v13, vcc, 1.0, v1, 1.0
	v_fmac_f32_e32 v23, v24, v23
	v_mul_f32_e32 v24, v13, v23
	v_fma_f32 v25, -v22, v24, v13
	v_fmac_f32_e32 v24, v25, v23
	v_fma_f32 v13, -v22, v24, v13
	v_div_fmas_f32 v13, v13, v23, v24
	v_div_fixup_f32 v22, v13, v1, 1.0
	v_pk_mul_f32 v[2:3], v[22:23], v[2:3] op_sel_hi:[0,1]
	v_pk_mul_f32 v[4:5], v[22:23], v[4:5] op_sel_hi:[0,1]
	v_pk_mul_f32 v[6:7], v[22:23], v[6:7] op_sel_hi:[0,1]
	v_pk_mul_f32 v[8:9], v[22:23], v[8:9] op_sel_hi:[0,1]
	v_cvt_pk_bf16_f32 v2, v2, v3
	v_cvt_pk_bf16_f32 v3, v4, v5
	v_cvt_pk_bf16_f32 v4, v6, v7
	v_cvt_pk_bf16_f32 v5, v8, v9
	global_store_dwordx4 v[230:231], v[2:5], off offset:1024
; DI unsigned pack2bf(float a, float b) { const f2_t v = {a, b}; return __builtin_bit_cast(unsigned, __builtin_convertvector(v, bf2_t)); }
; DI void phase5(const Params& P, char* smem) {
;     ...
;   for (long idx = (long)VB * 256 + VT; idx < (long)NTOK * 64; idx += (long)NVB * 256) {
;     const int dg = (int)idx & 7, h = (int)(idx >> 3) & 7; const long tok = idx >> 6;
;     const int l = (int)(tok & 8191); const int ownb = l >> 8; const int nv = ownb < 3 ? ownb : 3;
;     const long base = (tok * 8 + h) * 4;
;     float ls[4]; float mx = -3e38f;
; #pragma unroll
;     for (int s = 0; s < 4; ++s) { const bool ok = (s == 3) || (s < nv); ls[s] = ok ? Lse[base + s] : -3e38f; mx = fmaxf(mx, ls[s]); }
;     float acc[8]; float wsum = 0.f;
; #pragma unroll
;     for (int k = 0; k < 8; ++k) acc[k] = 0.f;
; #pragma unroll
;     for (int s = 0; s < 4; ++s) {
;       const bool ok = (s == 3) || (s < nv);
;       if (ok) {
;         const float w = __expf(ls[s] - mx); wsum += w;
;         uint4 o = *reinterpret_cast<const uint4*>(Opart + (base + s) * 64 + dg * 8);
;         acc[0] += w * __uint_as_float(o.x << 16); acc[1] += w * __uint_as_float(o.x & 0xffff0000u);
;         acc[2] += w * __uint_as_float(o.y << 16); acc[3] += w * __uint_as_float(o.y & 0xffff0000u);
;         acc[4] += w * __uint_as_float(o.z << 16); acc[5] += w * __uint_as_float(o.z & 0xffff0000u);
;         acc[6] += w * __uint_as_float(o.w << 16); acc[7] += w * __uint_as_float(o.w & 0xffff0000u);
;       }
;     }
;     const float inv = 1.f / wsum;
;     *reinterpret_cast<uint4*>(cat + tok * 1024 + 512 + h * 64 + dg * 8) =
;         make_uint4(pack2bf(acc[0] * inv, acc[1] * inv), pack2bf(acc[2] * inv, acc[3] * inv), pack2bf(acc[4] * inv, acc[5] * inv), pack2bf(acc[6] * inv, acc[7] * inv));
;   }
.Lp5_merge_loop:
	v_ashrrev_i64 v[16:17], 6, v[14:15]
	v_bfe_u32 v13, v14, 3, 3
	v_lshlrev_b64 v[20:21], 5, v[16:17]
	v_bfe_u32 v232, v16, 8, 5
	v_lshl_or_b32 v20, v13, 2, v20
	v_lshl_add_u64 v[22:23], v[20:21], 2, s[40:41]
	v_lshlrev_b64 v[18:19], 7, v[20:21]
	global_load_dwordx4 v[210:213], v[22:23], off
	v_lshl_add_u64 v[18:19], v[10:11], 0, v[18:19]
	global_load_dwordx4 v[214:217], v[18:19], off
	global_load_dwordx4 v[218:221], v[18:19], off offset:128
	global_load_dwordx4 v[222:225], v[18:19], off offset:256
	global_load_dwordx4 v[226:229], v[18:19], off offset:384
	v_lshlrev_b64 v[16:17], 11, v[16:17]
	v_lshlrev_b32_e32 v24, 7, v13
	v_mov_b32_e32 v25, v0
	v_lshl_add_u64 v[16:17], s[62:63], 0, v[16:17]
	v_mov_b32_e32 v13, v0
	v_lshl_add_u64 v[16:17], v[16:17], 0, v[24:25]
	v_lshl_add_u64 v[230:231], v[16:17], 0, v[12:13]
	v_lshl_add_u64 v[14:15], v[14:15], 0, s[66:67]
	s_waitcnt vmcnt(6)
	v_cmp_ne_u32_e64 s[4:5], 0, v38
	v_cmp_lt_u32_e64 s[6:7], 1, v38
	v_cmp_lt_u32_e64 s[8:9], 2, v38
	v_mov_b32_e32 v26, 0xff61b1e6
	v_cndmask_b32_e64 v27, v26, v234, s[4:5]
	v_cndmask_b32_e64 v28, v26, v235, s[6:7]
	v_cndmask_b32_e64 v29, v26, v236, s[8:9]
	v_max3_f32 v24, v27, s2, v28
	v_max3_f32 v24, v24, v29, v237
	v_sub_f32_e32 v1, v27, v24
	v_mul_f32_e32 v1, 0x3fb8aa3b, v1
	v_exp_f32_e32 v30, v1
	v_sub_f32_e32 v1, v28, v24
	v_mul_f32_e32 v1, 0x3fb8aa3b, v1
	v_exp_f32_e32 v32, v1
	v_sub_f32_e32 v1, v29, v24
	v_mul_f32_e32 v1, 0x3fb8aa3b, v1
	v_exp_f32_e32 v34, v1
	v_sub_f32_e32 v1, v237, v24
	v_mul_f32_e32 v1, 0x3fb8aa3b, v1
	v_exp_f32_e32 v48, v1
	v_cndmask_b32_e64 v238, 0, v238, s[4:5]
	v_cndmask_b32_e64 v239, 0, v239, s[4:5]
	v_cndmask_b32_e64 v240, 0, v240, s[4:5]
	v_cndmask_b32_e64 v241, 0, v241, s[4:5]
	v_cndmask_b32_e64 v242, 0, v242, s[6:7]
	v_cndmask_b32_e64 v243, 0, v243, s[6:7]
	v_cndmask_b32_e64 v244, 0, v244, s[6:7]
	v_cndmask_b32_e64 v245, 0, v245, s[6:7]
	v_cndmask_b32_e64 v246, 0, v246, s[8:9]
	v_cndmask_b32_e64 v247, 0, v247, s[8:9]
	v_cndmask_b32_e64 v248, 0, v248, s[8:9]
	v_cndmask_b32_e64 v249, 0, v249, s[8:9]
	v_add_f32_e32 v22, 0, v30
	v_add_f32_e32 v22, v32, v22
	v_add_f32_e32 v22, v34, v22
	v_add_f32_e32 v22, v48, v22
	v_lshlrev_b32_e32 v40, 16, v238
	v_and_b32_e32 v41, 0xffff0000, v238
	v_lshlrev_b32_e32 v42, 16, v239
	v_and_b32_e32 v43, 0xffff0000, v239
	v_lshlrev_b32_e32 v44, 16, v240
	v_and_b32_e32 v45, 0xffff0000, v240
	v_lshlrev_b32_e32 v46, 16, v241
	v_and_b32_e32 v47, 0xffff0000, v241
	v_pk_fma_f32 v[2:3], v[30:31], v[40:41], 0 op_sel_hi:[0,1,0]
	v_pk_fma_f32 v[4:5], v[30:31], v[42:43], 0 op_sel_hi:[0,1,0]
	v_pk_fma_f32 v[6:7], v[30:31], v[44:45], 0 op_sel_hi:[0,1,0]
	v_pk_fma_f32 v[8:9], v[30:31], v[46:47], 0 op_sel_hi:[0,1,0]
	v_lshlrev_b32_e32 v40, 16, v242
	v_and_b32_e32 v41, 0xffff0000, v242
	v_lshlrev_b32_e32 v42, 16, v243
	v_and_b32_e32 v43, 0xffff0000, v243
	v_lshlrev_b32_e32 v44, 16, v244
	v_and_b32_e32 v45, 0xffff0000, v244
	v_lshlrev_b32_e32 v46, 16, v245
	v_and_b32_e32 v47, 0xffff0000, v245
	v_pk_fma_f32 v[2:3], v[32:33], v[40:41], v[2:3] op_sel_hi:[0,1,1]
	v_pk_fma_f32 v[4:5], v[32:33], v[42:43], v[4:5] op_sel_hi:[0,1,1]
	v_pk_fma_f32 v[6:7], v[32:33], v[44:45], v[6:7] op_sel_hi:[0,1,1]
	v_pk_fma_f32 v[8:9], v[32:33], v[46:47], v[8:9] op_sel_hi:[0,1,1]
	v_lshlrev_b32_e32 v40, 16, v246
	v_and_b32_e32 v41, 0xffff0000, v246
	v_lshlrev_b32_e32 v42, 16, v247
	v_and_b32_e32 v43, 0xffff0000, v247
	v_lshlrev_b32_e32 v44, 16, v248
	v_and_b32_e32 v45, 0xffff0000, v248
	v_lshlrev_b32_e32 v46, 16, v249
	v_and_b32_e32 v47, 0xffff0000, v249
	v_pk_fma_f32 v[2:3], v[34:35], v[40:41], v[2:3] op_sel_hi:[0,1,1]
	v_pk_fma_f32 v[4:5], v[34:35], v[42:43], v[4:5] op_sel_hi:[0,1,1]
	v_pk_fma_f32 v[6:7], v[34:35], v[44:45], v[6:7] op_sel_hi:[0,1,1]
	v_pk_fma_f32 v[8:9], v[34:35], v[46:47], v[8:9] op_sel_hi:[0,1,1]
	v_lshlrev_b32_e32 v40, 16, v250
	v_and_b32_e32 v41, 0xffff0000, v250
	v_lshlrev_b32_e32 v42, 16, v251
	v_and_b32_e32 v43, 0xffff0000, v251
	v_lshlrev_b32_e32 v44, 16, v252
	v_and_b32_e32 v45, 0xffff0000, v252
	v_lshlrev_b32_e32 v46, 16, v253
	v_and_b32_e32 v47, 0xffff0000, v253
	v_pk_fma_f32 v[2:3], v[48:49], v[40:41], v[2:3] op_sel_hi:[0,1,1]
	v_pk_fma_f32 v[4:5], v[48:49], v[42:43], v[4:5] op_sel_hi:[0,1,1]
	v_pk_fma_f32 v[6:7], v[48:49], v[44:45], v[6:7] op_sel_hi:[0,1,1]
	v_pk_fma_f32 v[8:9], v[48:49], v[46:47], v[8:9] op_sel_hi:[0,1,1]
	v_mov_b32_e32 v1, v22
	v_div_scale_f32 v22, s[4:5], v1, v1, 1.0
	v_rcp_f32_e32 v23, v22
	s_nop 0
	v_fma_f32 v24, -v22, v23, 1.0
	v_div_scale_f32 v13, vcc, 1.0, v1, 1.0
	v_fmac_f32_e32 v23, v24, v23
	v_mul_f32_e32 v24, v13, v23
	v_fma_f32 v25, -v22, v24, v13
	v_fmac_f32_e32 v24, v25, v23
	v_fma_f32 v13, -v22, v24, v13
	v_div_fmas_f32 v13, v13, v23, v24
	v_div_fixup_f32 v22, v13, v1, 1.0
	v_pk_mul_f32 v[2:3], v[22:23], v[2:3] op_sel_hi:[0,1]
	v_pk_mul_f32 v[4:5], v[22:23], v[4:5] op_sel_hi:[0,1]
	v_pk_mul_f32 v[6:7], v[22:23], v[6:7] op_sel_hi:[0,1]
	v_pk_mul_f32 v[8:9], v[22:23], v[8:9] op_sel_hi:[0,1]
	v_cvt_pk_bf16_f32 v2, v2, v3
	v_cvt_pk_bf16_f32 v3, v4, v5
	v_cvt_pk_bf16_f32 v4, v6, v7
	v_cvt_pk_bf16_f32 v5, v8, v9
	global_store_dwordx4 v[36:37], v[2:5], off offset:1024
	v_ashrrev_i64 v[16:17], 6, v[14:15]
	v_bfe_u32 v13, v14, 3, 3
	v_lshlrev_b64 v[20:21], 5, v[16:17]
	v_bfe_u32 v38, v16, 8, 5
	v_lshl_or_b32 v20, v13, 2, v20
	v_lshl_add_u64 v[22:23], v[20:21], 2, s[40:41]
	v_lshlrev_b64 v[18:19], 7, v[20:21]
	global_load_dwordx4 v[234:237], v[22:23], off
	v_lshl_add_u64 v[18:19], v[10:11], 0, v[18:19]
	global_load_dwordx4 v[238:241], v[18:19], off
	global_load_dwordx4 v[242:245], v[18:19], off offset:128
	global_load_dwordx4 v[246:249], v[18:19], off offset:256
	global_load_dwordx4 v[250:253], v[18:19], off offset:384
	v_lshlrev_b64 v[16:17], 11, v[16:17]
	v_lshlrev_b32_e32 v24, 7, v13
	v_mov_b32_e32 v25, v0
	v_lshl_add_u64 v[16:17], s[62:63], 0, v[16:17]
	v_mov_b32_e32 v13, v0
	v_lshl_add_u64 v[16:17], v[16:17], 0, v[24:25]
	v_lshl_add_u64 v[36:37], v[16:17], 0, v[12:13]
	v_lshl_add_u64 v[14:15], v[14:15], 0, s[66:67]
	s_waitcnt vmcnt(6)
; DI unsigned pack2bf(float a, float b) { const f2_t v = {a, b}; return __builtin_bit_cast(unsigned, __builtin_convertvector(v, bf2_t)); }
; DI void phase5(const Params& P, char* smem) {
;     ...
;   for (long idx = (long)VB * 256 + VT; idx < (long)NTOK * 64; idx += (long)NVB * 256) {
;     const int dg = (int)idx & 7, h = (int)(idx >> 3) & 7; const long tok = idx >> 6;
;     const int l = (int)(tok & 8191); const int ownb = l >> 8; const int nv = ownb < 3 ? ownb : 3;
;     const long base = (tok * 8 + h) * 4;
;     float ls[4]; float mx = -3e38f;
; #pragma unroll
;     for (int s = 0; s < 4; ++s) { const bool ok = (s == 3) || (s < nv); ls[s] = ok ? Lse[base + s] : -3e38f; mx = fmaxf(mx, ls[s]); }
;     float acc[8]; float wsum = 0.f;
; #pragma unroll
;     for (int k = 0; k < 8; ++k) acc[k] = 0.f;
; #pragma unroll
;     for (int s = 0; s < 4; ++s) {
;       const bool ok = (s == 3) || (s < nv);
;       if (ok) {
;         const float w = __expf(ls[s] - mx); wsum += w;
;         uint4 o = *reinterpret_cast<const uint4*>(Opart + (base + s) * 64 + dg * 8);
;         acc[0] += w * __uint_as_float(o.x << 16); acc[1] += w * __uint_as_float(o.x & 0xffff0000u);
;         acc[2] += w * __uint_as_float(o.y << 16); acc[3] += w * __uint_as_float(o.y & 0xffff0000u);
;         acc[4] += w * __uint_as_float(o.z << 16); acc[5] += w * __uint_as_float(o.z & 0xffff0000u);
;         acc[6] += w * __uint_as_float(o.w << 16); acc[7] += w * __uint_as_float(o.w & 0xffff0000u);
;       }
;     }
;     const float inv = 1.f / wsum;
;     *reinterpret_cast<uint4*>(cat + tok * 1024 + 512 + h * 64 + dg * 8) =
;         make_uint4(pack2bf(acc[0] * inv, acc[1] * inv), pack2bf(acc[2] * inv, acc[3] * inv), pack2bf(acc[4] * inv, acc[5] * inv), pack2bf(acc[6] * inv, acc[7] * inv));
;   }
	v_cmp_ne_u32_e64 s[4:5], 0, v232
	v_cmp_lt_u32_e64 s[6:7], 1, v232
	v_cmp_lt_u32_e64 s[8:9], 2, v232
	v_mov_b32_e32 v26, 0xff61b1e6
	v_cndmask_b32_e64 v27, v26, v210, s[4:5]
	v_cndmask_b32_e64 v28, v26, v211, s[6:7]
	v_cndmask_b32_e64 v29, v26, v212, s[8:9]
	v_max3_f32 v24, v27, s2, v28
	v_max3_f32 v24, v24, v29, v213
	v_sub_f32_e32 v1, v27, v24
	v_mul_f32_e32 v1, 0x3fb8aa3b, v1
	v_exp_f32_e32 v30, v1
	v_sub_f32_e32 v1, v28, v24
	v_mul_f32_e32 v1, 0x3fb8aa3b, v1
	v_exp_f32_e32 v32, v1
	v_sub_f32_e32 v1, v29, v24
	v_mul_f32_e32 v1, 0x3fb8aa3b, v1
	v_exp_f32_e32 v34, v1
	v_sub_f32_e32 v1, v213, v24
	v_mul_f32_e32 v1, 0x3fb8aa3b, v1
	v_exp_f32_e32 v48, v1
	v_cndmask_b32_e64 v214, 0, v214, s[4:5]
	v_cndmask_b32_e64 v215, 0, v215, s[4:5]
	v_cndmask_b32_e64 v216, 0, v216, s[4:5]
	v_cndmask_b32_e64 v217, 0, v217, s[4:5]
	v_cndmask_b32_e64 v218, 0, v218, s[6:7]
	v_cndmask_b32_e64 v219, 0, v219, s[6:7]
	v_cndmask_b32_e64 v220, 0, v220, s[6:7]
	v_cndmask_b32_e64 v221, 0, v221, s[6:7]
	v_cndmask_b32_e64 v222, 0, v222, s[8:9]
	v_cndmask_b32_e64 v223, 0, v223, s[8:9]
	v_cndmask_b32_e64 v224, 0, v224, s[8:9]
	v_cndmask_b32_e64 v225, 0, v225, s[8:9]
	v_add_f32_e32 v22, 0, v30
	v_add_f32_e32 v22, v32, v22
	v_add_f32_e32 v22, v34, v22
	v_add_f32_e32 v22, v48, v22
	v_lshlrev_b32_e32 v40, 16, v214
	v_and_b32_e32 v41, 0xffff0000, v214
	v_lshlrev_b32_e32 v42, 16, v215
	v_and_b32_e32 v43, 0xffff0000, v215
	v_lshlrev_b32_e32 v44, 16, v216
	v_and_b32_e32 v45, 0xffff0000, v216
	v_lshlrev_b32_e32 v46, 16, v217
	v_and_b32_e32 v47, 0xffff0000, v217
	v_pk_fma_f32 v[2:3], v[30:31], v[40:41], 0 op_sel_hi:[0,1,0]
	v_pk_fma_f32 v[4:5], v[30:31], v[42:43], 0 op_sel_hi:[0,1,0]
	v_pk_fma_f32 v[6:7], v[30:31], v[44:45], 0 op_sel_hi:[0,1,0]
	v_pk_fma_f32 v[8:9], v[30:31], v[46:47], 0 op_sel_hi:[0,1,0]
	v_lshlrev_b32_e32 v40, 16, v218
	v_and_b32_e32 v41, 0xffff0000, v218
	v_lshlrev_b32_e32 v42, 16, v219
	v_and_b32_e32 v43, 0xffff0000, v219
	v_lshlrev_b32_e32 v44, 16, v220
	v_and_b32_e32 v45, 0xffff0000, v220
	v_lshlrev_b32_e32 v46, 16, v221
	v_and_b32_e32 v47, 0xffff0000, v221
	v_pk_fma_f32 v[2:3], v[32:33], v[40:41], v[2:3] op_sel_hi:[0,1,1]
	v_pk_fma_f32 v[4:5], v[32:33], v[42:43], v[4:5] op_sel_hi:[0,1,1]
	v_pk_fma_f32 v[6:7], v[32:33], v[44:45], v[6:7] op_sel_hi:[0,1,1]
	v_pk_fma_f32 v[8:9], v[32:33], v[46:47], v[8:9] op_sel_hi:[0,1,1]
	v_lshlrev_b32_e32 v40, 16, v222
	v_and_b32_e32 v41, 0xffff0000, v222
	v_lshlrev_b32_e32 v42, 16, v223
	v_and_b32_e32 v43, 0xffff0000, v223
	v_lshlrev_b32_e32 v44, 16, v224
	v_and_b32_e32 v45, 0xffff0000, v224
	v_lshlrev_b32_e32 v46, 16, v225
	v_and_b32_e32 v47, 0xffff0000, v225
	v_pk_fma_f32 v[2:3], v[34:35], v[40:41], v[2:3] op_sel_hi:[0,1,1]
	v_pk_fma_f32 v[4:5], v[34:35], v[42:43], v[4:5] op_sel_hi:[0,1,1]
	v_pk_fma_f32 v[6:7], v[34:35], v[44:45], v[6:7] op_sel_hi:[0,1,1]
	v_pk_fma_f32 v[8:9], v[34:35], v[46:47], v[8:9] op_sel_hi:[0,1,1]
	v_lshlrev_b32_e32 v40, 16, v226
	v_and_b32_e32 v41, 0xffff0000, v226
	v_lshlrev_b32_e32 v42, 16, v227
	v_and_b32_e32 v43, 0xffff0000, v227
	v_lshlrev_b32_e32 v44, 16, v228
	v_and_b32_e32 v45, 0xffff0000, v228
	v_lshlrev_b32_e32 v46, 16, v229
	v_and_b32_e32 v47, 0xffff0000, v229
	v_pk_fma_f32 v[2:3], v[48:49], v[40:41], v[2:3] op_sel_hi:[0,1,1]
	v_pk_fma_f32 v[4:5], v[48:49], v[42:43], v[4:5] op_sel_hi:[0,1,1]
	v_pk_fma_f32 v[6:7], v[48:49], v[44:45], v[6:7] op_sel_hi:[0,1,1]
	v_pk_fma_f32 v[8:9], v[48:49], v[46:47], v[8:9] op_sel_hi:[0,1,1]
	v_mov_b32_e32 v1, v22
	v_div_scale_f32 v22, s[4:5], v1, v1, 1.0
	v_rcp_f32_e32 v23, v22
	s_nop 0
	v_fma_f32 v24, -v22, v23, 1.0
	v_div_scale_f32 v13, vcc, 1.0, v1, 1.0
	v_fmac_f32_e32 v23, v24, v23
	v_mul_f32_e32 v24, v13, v23
	v_fma_f32 v25, -v22, v24, v13
	v_fmac_f32_e32 v24, v25, v23
	v_fma_f32 v13, -v22, v24, v13
	v_div_fmas_f32 v13, v13, v23, v24
	v_div_fixup_f32 v22, v13, v1, 1.0
	v_pk_mul_f32 v[2:3], v[22:23], v[2:3] op_sel_hi:[0,1]
	v_pk_mul_f32 v[4:5], v[22:23], v[4:5] op_sel_hi:[0,1]
	v_pk_mul_f32 v[6:7], v[22:23], v[6:7] op_sel_hi:[0,1]
	v_pk_mul_f32 v[8:9], v[22:23], v[8:9] op_sel_hi:[0,1]
	v_cvt_pk_bf16_f32 v2, v2, v3
	v_cvt_pk_bf16_f32 v3, v4, v5
	v_cvt_pk_bf16_f32 v4, v6, v7
	v_cvt_pk_bf16_f32 v5, v8, v9
	global_store_dwordx4 v[230:231], v[2:5], off offset:1024
	s_sub_i32 s12, s12, 1
	s_cmp_lg_u32 s12, 0
	s_cbranch_scc1 .Lp5_merge_loop
; DI unsigned pack2bf(float a, float b) { const f2_t v = {a, b}; return __builtin_bit_cast(unsigned, __builtin_convertvector(v, bf2_t)); }
; DI void phase5(const Params& P, char* smem) {
;     ...
;   for (long idx = (long)VB * 256 + VT; idx < (long)NTOK * 64; idx += (long)NVB * 256) {
;     const int dg = (int)idx & 7, h = (int)(idx >> 3) & 7; const long tok = idx >> 6;
;     const int l = (int)(tok & 8191); const int ownb = l >> 8; const int nv = ownb < 3 ? ownb : 3;
;     const long base = (tok * 8 + h) * 4;
;     float ls[4]; float mx = -3e38f;
; #pragma unroll
;     for (int s = 0; s < 4; ++s) { const bool ok = (s == 3) || (s < nv); ls[s] = ok ? Lse[base + s] : -3e38f; mx = fmaxf(mx, ls[s]); }
;     float acc[8]; float wsum = 0.f;
; #pragma unroll
;     for (int k = 0; k < 8; ++k) acc[k] = 0.f;
; #pragma unroll
;     for (int s = 0; s < 4; ++s) {
;       const bool ok = (s == 3) || (s < nv);
;       if (ok) {
;         const float w = __expf(ls[s] - mx); wsum += w;
;         uint4 o = *reinterpret_cast<const uint4*>(Opart + (base + s) * 64 + dg * 8);
;         acc[0] += w * __uint_as_float(o.x << 16); acc[1] += w * __uint_as_float(o.x & 0xffff0000u);
;         acc[2] += w * __uint_as_float(o.y << 16); acc[3] += w * __uint_as_float(o.y & 0xffff0000u);
;         acc[4] += w * __uint_as_float(o.z << 16); acc[5] += w * __uint_as_float(o.z & 0xffff0000u);
;         acc[6] += w * __uint_as_float(o.w << 16); acc[7] += w * __uint_as_float(o.w & 0xffff0000u);
;       }
;     }
;     const float inv = 1.f / wsum;
;     *reinterpret_cast<uint4*>(cat + tok * 1024 + 512 + h * 64 + dg * 8) =
;         make_uint4(pack2bf(acc[0] * inv, acc[1] * inv), pack2bf(acc[2] * inv, acc[3] * inv), pack2bf(acc[4] * inv, acc[5] * inv), pack2bf(acc[6] * inv, acc[7] * inv));
;   }
	s_waitcnt vmcnt(1)
	v_cmp_ne_u32_e64 s[4:5], 0, v38
	v_cmp_lt_u32_e64 s[6:7], 1, v38
	v_cmp_lt_u32_e64 s[8:9], 2, v38
	v_mov_b32_e32 v26, 0xff61b1e6
	v_cndmask_b32_e64 v27, v26, v234, s[4:5]
	v_cndmask_b32_e64 v28, v26, v235, s[6:7]
	v_cndmask_b32_e64 v29, v26, v236, s[8:9]
	v_max3_f32 v24, v27, s2, v28
	v_max3_f32 v24, v24, v29, v237
	v_sub_f32_e32 v1, v27, v24
	v_mul_f32_e32 v1, 0x3fb8aa3b, v1
	v_exp_f32_e32 v30, v1
	v_sub_f32_e32 v1, v28, v24
	v_mul_f32_e32 v1, 0x3fb8aa3b, v1
	v_exp_f32_e32 v32, v1
	v_sub_f32_e32 v1, v29, v24
	v_mul_f32_e32 v1, 0x3fb8aa3b, v1
	v_exp_f32_e32 v34, v1
	v_sub_f32_e32 v1, v237, v24
	v_mul_f32_e32 v1, 0x3fb8aa3b, v1
	v_exp_f32_e32 v48, v1
	v_cndmask_b32_e64 v238, 0, v238, s[4:5]
	v_cndmask_b32_e64 v239, 0, v239, s[4:5]
	v_cndmask_b32_e64 v240, 0, v240, s[4:5]
	v_cndmask_b32_e64 v241, 0, v241, s[4:5]
	v_cndmask_b32_e64 v242, 0, v242, s[6:7]
	v_cndmask_b32_e64 v243, 0, v243, s[6:7]
	v_cndmask_b32_e64 v244, 0, v244, s[6:7]
	v_cndmask_b32_e64 v245, 0, v245, s[6:7]
	v_cndmask_b32_e64 v246, 0, v246, s[8:9]
	v_cndmask_b32_e64 v247, 0, v247, s[8:9]
	v_cndmask_b32_e64 v248, 0, v248, s[8:9]
	v_cndmask_b32_e64 v249, 0, v249, s[8:9]
	v_add_f32_e32 v22, 0, v30
	v_add_f32_e32 v22, v32, v22
	v_add_f32_e32 v22, v34, v22
	v_add_f32_e32 v22, v48, v22
	v_lshlrev_b32_e32 v40, 16, v238
	v_and_b32_e32 v41, 0xffff0000, v238
	v_lshlrev_b32_e32 v42, 16, v239
	v_and_b32_e32 v43, 0xffff0000, v239
	v_lshlrev_b32_e32 v44, 16, v240
	v_and_b32_e32 v45, 0xffff0000, v240
	v_lshlrev_b32_e32 v46, 16, v241
	v_and_b32_e32 v47, 0xffff0000, v241
	v_pk_fma_f32 v[2:3], v[30:31], v[40:41], 0 op_sel_hi:[0,1,0]
	v_pk_fma_f32 v[4:5], v[30:31], v[42:43], 0 op_sel_hi:[0,1,0]
	v_pk_fma_f32 v[6:7], v[30:31], v[44:45], 0 op_sel_hi:[0,1,0]
	v_pk_fma_f32 v[8:9], v[30:31], v[46:47], 0 op_sel_hi:[0,1,0]
	v_lshlrev_b32_e32 v40, 16, v242
	v_and_b32_e32 v41, 0xffff0000, v242
	v_lshlrev_b32_e32 v42, 16, v243
	v_and_b32_e32 v43, 0xffff0000, v243
	v_lshlrev_b32_e32 v44, 16, v244
	v_and_b32_e32 v45, 0xffff0000, v244
	v_lshlrev_b32_e32 v46, 16, v245
	v_and_b32_e32 v47, 0xffff0000, v245
	v_pk_fma_f32 v[2:3], v[32:33], v[40:41], v[2:3] op_sel_hi:[0,1,1]
	v_pk_fma_f32 v[4:5], v[32:33], v[42:43], v[4:5] op_sel_hi:[0,1,1]
	v_pk_fma_f32 v[6:7], v[32:33], v[44:45], v[6:7] op_sel_hi:[0,1,1]
	v_pk_fma_f32 v[8:9], v[32:33], v[46:47], v[8:9] op_sel_hi:[0,1,1]
	v_lshlrev_b32_e32 v40, 16, v246
	v_and_b32_e32 v41, 0xffff0000, v246
	v_lshlrev_b32_e32 v42, 16, v247
	v_and_b32_e32 v43, 0xffff0000, v247
	v_lshlrev_b32_e32 v44, 16, v248
	v_and_b32_e32 v45, 0xffff0000, v248
	v_lshlrev_b32_e32 v46, 16, v249
	v_and_b32_e32 v47, 0xffff0000, v249
	v_pk_fma_f32 v[2:3], v[34:35], v[40:41], v[2:3] op_sel_hi:[0,1,1]
	v_pk_fma_f32 v[4:5], v[34:35], v[42:43], v[4:5] op_sel_hi:[0,1,1]
	v_pk_fma_f32 v[6:7], v[34:35], v[44:45], v[6:7] op_sel_hi:[0,1,1]
	v_pk_fma_f32 v[8:9], v[34:35], v[46:47], v[8:9] op_sel_hi:[0,1,1]
	v_lshlrev_b32_e32 v40, 16, v250
	v_and_b32_e32 v41, 0xffff0000, v250
	v_lshlrev_b32_e32 v42, 16, v251
	v_and_b32_e32 v43, 0xffff0000, v251
	v_lshlrev_b32_e32 v44, 16, v252
	v_and_b32_e32 v45, 0xffff0000, v252
	v_lshlrev_b32_e32 v46, 16, v253
	v_and_b32_e32 v47, 0xffff0000, v253
	v_pk_fma_f32 v[2:3], v[48:49], v[40:41], v[2:3] op_sel_hi:[0,1,1]
	v_pk_fma_f32 v[4:5], v[48:49], v[42:43], v[4:5] op_sel_hi:[0,1,1]
	v_pk_fma_f32 v[6:7], v[48:49], v[44:45], v[6:7] op_sel_hi:[0,1,1]
	v_pk_fma_f32 v[8:9], v[48:49], v[46:47], v[8:9] op_sel_hi:[0,1,1]
	v_mov_b32_e32 v1, v22
	v_div_scale_f32 v22, s[4:5], v1, v1, 1.0
	v_rcp_f32_e32 v23, v22
	s_nop 0
	v_fma_f32 v24, -v22, v23, 1.0
	v_div_scale_f32 v13, vcc, 1.0, v1, 1.0
	v_fmac_f32_e32 v23, v24, v23
	v_mul_f32_e32 v24, v13, v23
	v_fma_f32 v25, -v22, v24, v13
	v_fmac_f32_e32 v24, v25, v23
	v_fma_f32 v13, -v22, v24, v13
	v_div_fmas_f32 v13, v13, v23, v24
	v_div_fixup_f32 v22, v13, v1, 1.0
	v_pk_mul_f32 v[2:3], v[22:23], v[2:3] op_sel_hi:[0,1]
	v_pk_mul_f32 v[4:5], v[22:23], v[4:5] op_sel_hi:[0,1]
	v_pk_mul_f32 v[6:7], v[22:23], v[6:7] op_sel_hi:[0,1]
	v_pk_mul_f32 v[8:9], v[22:23], v[8:9] op_sel_hi:[0,1]
	v_cvt_pk_bf16_f32 v2, v2, v3
	v_cvt_pk_bf16_f32 v3, v4, v5
	v_cvt_pk_bf16_f32 v4, v6, v7
	v_cvt_pk_bf16_f32 v5, v8, v9
	global_store_dwordx4 v[36:37], v[2:5], off offset:1024
